# mixer staging: early warm-up loads of the small parameter vectors (k/q/sgu norm gains, rel_bias, sinks) so the late dependent loads hit cache
# speedup vs baseline: 1.0060x; 1.0060x over previous
; __device__ __forceinline__ void mixer_phase256(const Args& A, int l, int vc, const bf16* Z, bf16* MIX, ss_t* ssa, ss_t* ssb, unsigned char* lds, int tid, int wid, int lane) {
;     ...
;     const int gx = vc & 7, gj = vc >> 3;
;     const int n = 8 * gx + (gj >> 2), kvh = gj & 3, h = gj & 15, cb = 8 * gx + 4 * (gj >> 4);
;     const int fr = lane & 15, fq = lane >> 4;
;     const bool isK = tid < 256; const int arow = tid & 255; const int atok = (n - 1) * 128 + arow;
;     u32x4 aw[8], sw[8];
;     { const bf16* ap = Z + (size_t)(atok < 0 ? 0 : atok) * INW + (isK ? KCOL : VCOL) + kvh * 64;
; #pragma unroll
;       for (int c = 0; c < 8; ++c) aw[c] = *(const u32x4*)(ap + 8 * c); }
;     const int srow = tid & 127, sj = tid >> 7;
;     { const bf16* sp = Z + (size_t)((cb + sj) * 128 + srow) * INW + 1024 + h * 64;
; #pragma unroll
;       for (int c = 0; c < 8; ++c) sw[c] = *(const u32x4*)(sp + 8 * c); }
.LBB0_505:
	s_and_b64 vcc, exec, s[2:3]
	s_cbranch_vccz .LBB0_803
	v_lshlrev_b32_e32 v253, 2, v174
	v_lshlrev_b32_e32 v251, 2, v113
	s_lshl_b32 s2, s78, 8
	v_readlane_b32 s100, v250, 30
	v_readlane_b32 s101, v250, 31
	v_readlane_b32 s3, v248, 3
	s_nop 0
	s_add_u32 s100, s100, s2
	s_addc_u32 s101, s101, 0
	s_nop 0
	global_load_dword v254, v253, s[100:101]
	v_readlane_b32 s100, v250, 26
	v_readlane_b32 s101, v250, 27
	s_nop 0
	s_add_u32 s100, s100, s2
	s_addc_u32 s101, s101, 0
	s_nop 0
	global_load_dword v255, v253, s[100:101]
	s_lshl_b32 s2, s78, 4
	s_or_b32 s2, s2, s3
	s_lshl_b32 s2, s2, 8
	v_readlane_b32 s100, v250, 20
	v_readlane_b32 s101, v250, 21
	s_nop 0
	s_add_u32 s100, s100, s2
	s_addc_u32 s101, s101, 0
	s_nop 0
	global_load_dword v254, v253, s[100:101]
	v_readlane_b32 s100, v250, 14
	v_readlane_b32 s101, v250, 15
	s_nop 4
	global_load_dword v255, v251, s[100:101]
	v_readlane_b32 s100, v250, 32
	v_readlane_b32 s101, v250, 33
	s_nop 4
	global_load_dword v254, v253, s[100:101]
	v_and_b32_e32 v178, 0xff, v113
	v_readlane_b32 s2, v248, 2
	v_mov_b64_e32 v[0:1], s[82:83]
	v_mov_b32_e32 v5, v2
	v_add_u32_e32 v100, s2, v178
	v_max_i32_e32 v3, 0, v100
	v_mad_u64_u32 v[0:1], s[2:3], v3, s85, v[0:1]
	s_movk_i32 s2, 0x100
	s_nop 0
	v_cmp_gt_i32_e32 vcc, s2, v113
	v_readlane_b32 s2, v247, 25
	v_readlane_b32 s3, v247, 26
	v_cndmask_b32_e32 v4, v210, v211, vcc
	v_lshl_add_u64 v[0:1], v[0:1], 0, v[4:5]
	s_mov_b32 s4, s2
	s_mov_b32 s5, s77
	v_writelane_b32 v247, s2, 25
	v_lshl_add_u64 v[0:1], v[0:1], 0, s[4:5]
	v_ashrrev_i32_e32 v177, 7, v113
	v_writelane_b32 v247, s3, 26
	v_readlane_b32 s2, v248, 6
	global_load_dwordx4 v[76:79], v[0:1], off offset:48
	global_load_dwordx4 v[80:83], v[0:1], off offset:32
	global_load_dwordx4 v[84:87], v[0:1], off offset:16
	global_load_dwordx4 v[88:91], v[0:1], off
	global_load_dwordx4 v[92:95], v[0:1], off offset:112
	global_load_dwordx4 v[96:99], v[0:1], off offset:96
	global_load_dwordx4 v[68:71], v[0:1], off offset:80
	global_load_dwordx4 v[72:75], v[0:1], off offset:64
	v_add_u32_e32 v0, s2, v177
	v_readlane_b32 s2, v248, 4
	v_and_b32_e32 v3, 0x7f, v113
	v_readlane_b32 s3, v248, 5
	v_lshl_or_b32 v4, v0, 7, v3
	s_lshl_b32 s37, s78, 4
	v_mov_b64_e32 v[0:1], s[2:3]
	v_mad_i64_i32 v[0:1], s[2:3], v4, s85, v[0:1]
	global_load_dwordx4 v[44:47], v[0:1], off offset:2096
	global_load_dwordx4 v[48:51], v[0:1], off offset:2080
	global_load_dwordx4 v[52:55], v[0:1], off offset:2064
	global_load_dwordx4 v[56:59], v[0:1], off offset:2048
	global_load_dwordx4 v[60:63], v[0:1], off offset:2160
	global_load_dwordx4 v[64:67], v[0:1], off offset:2144
	global_load_dwordx4 v[4:7], v[0:1], off offset:2128
	global_load_dwordx4 v[8:11], v[0:1], off offset:2112
	v_readlane_b32 s4, v248, 3
	s_or_b32 s38, s37, s4
	v_and_b32_e32 v175, 15, v113
	s_ashr_i32 s36, s17, 7
	s_lshl_b32 s4, s38, 16
	v_lshl_or_b32 v114, s73, 4, v175
	s_add_u32 s4, s50, s4
	v_ashrrev_i32_e32 v115, 31, v114
	s_addc_u32 s5, s51, 0
	v_lshrrev_b32_e32 v176, 4, v174
	v_lshlrev_b64 v[0:1], 9, v[114:115]
	s_cmp_gt_i32 s36, -1
	s_movk_i32 s2, 0xff
	v_lshl_add_u64 v[0:1], s[4:5], 0, v[0:1]
	v_lshlrev_b32_e32 v12, 5, v176
	v_mov_b32_e32 v13, v2
	s_cselect_b64 s[8:9], -1, 0
	v_cmp_lt_i32_e64 s[2:3], s2, v113
	v_lshl_add_u64 v[0:1], v[0:1], 0, v[12:13]
	v_mov_b32_e32 v16, 0
	s_and_b64 vcc, exec, s[8:9]
	v_mov_b32_e32 v40, 0
	v_mov_b32_e32 v41, 0
	v_mov_b32_e32 v42, 0
	v_mov_b32_e32 v43, 0
	v_mov_b32_e32 v36, 0
	v_mov_b32_e32 v37, 0
	v_mov_b32_e32 v38, 0
	v_mov_b32_e32 v39, 0
	s_cbranch_vccz .LBB0_508
	global_load_dwordx4 v[40:43], v[0:1], off
	global_load_dwordx4 v[36:39], v[0:1], off offset:16

; __global__ void __launch_bounds__(NWAVES * 64, 2) fwd_kernel(Args A) {
	.amdhsa_kernel _Z10fwd_kernel4Args
		.amdhsa_group_segment_fixed_size 0
		.amdhsa_private_segment_fixed_size 0
		.amdhsa_kernarg_size 416
		.amdhsa_user_sgpr_count 2
		.amdhsa_user_sgpr_dispatch_ptr 0
		.amdhsa_user_sgpr_queue_ptr 0
		.amdhsa_user_sgpr_kernarg_segment_ptr 1
		.amdhsa_user_sgpr_dispatch_id 0
		.amdhsa_user_sgpr_kernarg_preload_length 0
		.amdhsa_user_sgpr_kernarg_preload_offset 0
		.amdhsa_user_sgpr_private_segment_size 0
		.amdhsa_uses_dynamic_stack 0
		.amdhsa_enable_private_segment 0
		.amdhsa_system_sgpr_workgroup_id_x 1
		.amdhsa_system_sgpr_workgroup_id_y 0
		.amdhsa_system_sgpr_workgroup_id_z 0
		.amdhsa_system_sgpr_workgroup_info 0
		.amdhsa_system_vgpr_workitem_id 2
		.amdhsa_next_free_vgpr 256
		.amdhsa_next_free_sgpr 102
		.amdhsa_accum_offset 256
		.amdhsa_reserve_vcc 1
		.amdhsa_float_round_mode_32 0
		.amdhsa_float_round_mode_16_64 0
		.amdhsa_float_denorm_mode_32 3
		.amdhsa_float_denorm_mode_16_64 3
		.amdhsa_dx10_clamp 1
		.amdhsa_ieee_mode 1
		.amdhsa_fp16_overflow 0
		.amdhsa_tg_split 0
		.amdhsa_exception_fp_ieee_invalid_op 0
		.amdhsa_exception_fp_denorm_src 0
		.amdhsa_exception_fp_ieee_div_zero 0
		.amdhsa_exception_fp_ieee_overflow 0
		.amdhsa_exception_fp_ieee_underflow 0
		.amdhsa_exception_fp_ieee_inexact 0
		.amdhsa_exception_int_div_zero 0
	.end_amdhsa_kernel

; __global__ void __launch_bounds__(NWAVES * 64, 2) fwd_kernel(Args A) {
amdhsa.kernels:
  - .agpr_count:     0
    .args:
      - .offset:         0
        .size:           160
        .value_kind:     by_value
      - .offset:         160
        .size:           4
        .value_kind:     hidden_block_count_x
      - .offset:         164
        .size:           4
        .value_kind:     hidden_block_count_y
      - .offset:         168
        .size:           4
        .value_kind:     hidden_block_count_z
      - .offset:         172
        .size:           2
        .value_kind:     hidden_group_size_x
      - .offset:         174
        .size:           2
        .value_kind:     hidden_group_size_y
      - .offset:         176
        .size:           2
        .value_kind:     hidden_group_size_z
      - .offset:         178
        .size:           2
        .value_kind:     hidden_remainder_x
      - .offset:         180
        .size:           2
        .value_kind:     hidden_remainder_y
      - .offset:         182
        .size:           2
        .value_kind:     hidden_remainder_z
      - .offset:         200
        .size:           8
        .value_kind:     hidden_global_offset_x
      - .offset:         208
        .size:           8
        .value_kind:     hidden_global_offset_y
      - .offset:         216
        .size:           8
        .value_kind:     hidden_global_offset_z
      - .offset:         224
        .size:           2
        .value_kind:     hidden_grid_dims
      - .offset:         248
        .size:           8
        .value_kind:     hidden_multigrid_sync_arg
      - .offset:         280
        .size:           4
        .value_kind:     hidden_dynamic_lds_size
    .group_segment_fixed_size: 0
    .kernarg_segment_align: 8
    .kernarg_segment_size: 416
    .language:       OpenCL C
    .language_version:
      - 2
      - 0
    .max_flat_workgroup_size: 512
    .name:           _Z10fwd_kernel4Args
    .private_segment_fixed_size: 0
    .sgpr_count:     108
    .sgpr_spill_count: 274
    .symbol:         _Z10fwd_kernel4Args.kd
    .uniform_work_group_size: 1
    .uses_dynamic_stack: false
    .vgpr_count:     256
    .vgpr_spill_count: 0
    .wavefront_size: 64
